# sl0 with the poll-loop s_sleep instructions removed entirely
# baseline (speedup 1.0000x reference)
.LBB0_335:
	v_mov_b64_e32 v[14:15], s[34:35]
	flat_load_dword v12, v[14:15] offset:1024 sc1
	s_waitcnt lgkmcnt(0)
	flat_load_dword v0, v[14:15] offset:1280 sc1
	flat_load_dword v2, v[14:15] offset:1536 sc1
	flat_load_dword v3, v[14:15] offset:1792 sc1
	flat_load_dword v4, v[14:15] offset:2048 sc1
	flat_load_dword v5, v[14:15] offset:2304 sc1
	flat_load_dword v6, v[14:15] offset:2560 sc1
	flat_load_dword v7, v[14:15] offset:2816 sc1
	flat_load_dword v8, v[14:15] offset:3072 sc1
	flat_load_dword v9, v[14:15] offset:3328 sc1
	flat_load_dword v10, v[14:15] offset:3584 sc1
	flat_load_dword v11, v[14:15] offset:3840 sc1
	v_mov_b64_e32 v[14:15], s[0:1]
	flat_load_dword v13, v[14:15] sc1
	v_mov_b64_e32 v[14:15], s[4:5]
	flat_load_dword v14, v[14:15] sc1
	v_mov_b64_e32 v[16:17], s[6:7]
	flat_load_dword v15, v[16:17] sc1
	v_mov_b64_e32 v[16:17], s[8:9]
	flat_load_dword v16, v[16:17] sc1
	v_readlane_b32 s18, v254, 12
	s_or_b64 s[16:17], s[16:17], exec
	s_or_b64 s[14:15], s[14:15], exec
	s_waitcnt vmcnt(0) lgkmcnt(0)
	v_add_u32_e32 v17, v0, v12
	v_add_u32_e32 v17, v17, v2
	v_add_u32_e32 v17, v17, v3
	v_add_u32_e32 v17, v17, v4
	v_add_u32_e32 v17, v17, v5
	v_add_u32_e32 v17, v17, v6
	v_add_u32_e32 v17, v17, v7
	v_add_u32_e32 v17, v17, v8
	v_add_u32_e32 v17, v17, v9
	v_add_u32_e32 v17, v17, v10
	v_add_u32_e32 v17, v17, v11
	v_add_u32_e32 v17, v17, v13
	v_add_u32_e32 v17, v17, v14
	v_add_u32_e32 v17, v17, v15
	v_add_u32_e32 v17, v17, v16
	v_cmp_ne_u32_e32 vcc, s18, v17
	s_and_saveexec_b64 s[18:19], vcc
	s_cbranch_execz .LBB0_334
	s_and_b32 s22, s28, 0xff
	s_mov_b64 s[20:21], -1
	s_cmp_eq_u32 s22, 0
	s_mov_b64 s[24:25], -1
	s_mov_b64 s[22:23], -1
	s_cbranch_scc1 .LBB0_338
	s_and_saveexec_b64 s[26:27], s[24:25]
	s_cbranch_execz .LBB0_333
	s_branch .LBB0_341

.LBB0_349:
	s_and_b32 s16, s23, 0xff
	s_mov_b64 s[14:15], -1
	s_cmp_lg_u32 s16, 0
	s_mov_b64 s[16:17], -1
	s_cbranch_scc1 .LBB0_353
	v_mov_b64_e32 v[4:5], s[34:35]
	flat_load_dword v0, v[4:5] offset:512 sc1
	s_mov_b64 s[16:17], 0
	s_mov_b64 s[18:19], -1
	s_waitcnt vmcnt(0) lgkmcnt(0)
	v_cmp_eq_u32_e32 vcc, 0, v0
	s_and_saveexec_b64 s[20:21], vcc
	s_cmp_lt_u32 s23, 0x40001
	s_cselect_b64 s[16:17], -1, 0
	s_xor_b64 s[18:19], exec, -1
	s_and_b64 s[16:17], s[16:17], exec
	s_or_b64 exec, exec, s[20:21]

.LBB0_363:
	s_and_b32 s16, s23, 0xff
	s_mov_b64 s[14:15], -1
	s_cmp_lg_u32 s16, 0
	s_mov_b64 s[18:19], -1
	s_cbranch_scc0 .LBB0_365
	s_and_saveexec_b64 s[20:21], s[18:19]
	s_cbranch_execz .LBB0_362
	s_branch .LBB0_368

.LBB0_383:
	global_load_dword v2, v1, s[2:3] offset:32 sc1
	s_waitcnt vmcnt(0)
	v_and_b32_e32 v2, 0xffff0000, v2
	v_cmp_ne_u32_e32 vcc, v2, v0
	s_or_b64 s[4:5], vcc, s[4:5]
	s_andn2_b64 exec, exec, s[4:5]
	s_cbranch_execnz .LBB0_383

.LBB0_529:
	v_mov_b64_e32 v[12:13], s[34:35]
	flat_load_dword v2, v[12:13] offset:1024 sc1
	s_waitcnt lgkmcnt(0)
	flat_load_dword v0, v[12:13] offset:1280 sc1
	flat_load_dword v3, v[12:13] offset:1536 sc1
	flat_load_dword v4, v[12:13] offset:1792 sc1
	flat_load_dword v5, v[12:13] offset:2048 sc1
	flat_load_dword v6, v[12:13] offset:2304 sc1
	flat_load_dword v7, v[12:13] offset:2560 sc1
	flat_load_dword v8, v[12:13] offset:2816 sc1
	flat_load_dword v9, v[12:13] offset:3072 sc1
	flat_load_dword v10, v[12:13] offset:3328 sc1
	flat_load_dword v11, v[12:13] offset:3584 sc1
	s_nop 0
	flat_load_dword v12, v[12:13] offset:3840 sc1
	v_mov_b64_e32 v[14:15], s[0:1]
	flat_load_dword v13, v[14:15] sc1
	v_mov_b64_e32 v[14:15], s[4:5]
	flat_load_dword v14, v[14:15] sc1
	v_mov_b64_e32 v[16:17], s[6:7]
	flat_load_dword v15, v[16:17] sc1
	v_mov_b64_e32 v[16:17], s[8:9]
	flat_load_dword v16, v[16:17] sc1
	v_readlane_b32 s18, v254, 12
	s_or_b64 s[16:17], s[16:17], exec
	s_or_b64 s[14:15], s[14:15], exec
	s_waitcnt vmcnt(0) lgkmcnt(0)
	v_add_u32_e32 v17, v0, v2
	v_add_u32_e32 v17, v17, v3
	v_add_u32_e32 v17, v17, v4
	v_add_u32_e32 v17, v17, v5
	v_add_u32_e32 v17, v17, v6
	v_add_u32_e32 v17, v17, v7
	v_add_u32_e32 v17, v17, v8
	v_add_u32_e32 v17, v17, v9
	v_add_u32_e32 v17, v17, v10
	v_add_u32_e32 v17, v17, v11
	v_add_u32_e32 v17, v17, v12
	v_add_u32_e32 v17, v17, v13
	v_add_u32_e32 v17, v17, v14
	v_add_u32_e32 v17, v17, v15
	v_add_u32_e32 v17, v17, v16
	v_cmp_ne_u32_e32 vcc, s18, v17
	s_and_saveexec_b64 s[18:19], vcc
	s_cbranch_execz .LBB0_528
	s_and_b32 s22, s28, 0xff
	s_mov_b64 s[20:21], -1
	s_cmp_eq_u32 s22, 0
	s_mov_b64 s[24:25], -1
	s_mov_b64 s[22:23], -1
	s_cbranch_scc1 .LBB0_532
	s_and_saveexec_b64 s[26:27], s[24:25]
	s_cbranch_execz .LBB0_527
	s_branch .LBB0_535

.LBB0_1023:
	v_mov_b64_e32 v[12:13], s[34:35]
	flat_load_dword v2, v[12:13] offset:1024 sc1
	s_waitcnt lgkmcnt(0)
	flat_load_dword v0, v[12:13] offset:1280 sc1
	flat_load_dword v3, v[12:13] offset:1536 sc1
	flat_load_dword v4, v[12:13] offset:1792 sc1
	flat_load_dword v5, v[12:13] offset:2048 sc1
	flat_load_dword v6, v[12:13] offset:2304 sc1
	flat_load_dword v7, v[12:13] offset:2560 sc1
	flat_load_dword v8, v[12:13] offset:2816 sc1
	flat_load_dword v9, v[12:13] offset:3072 sc1
	flat_load_dword v10, v[12:13] offset:3328 sc1
	flat_load_dword v11, v[12:13] offset:3584 sc1
	s_nop 0
	flat_load_dword v12, v[12:13] offset:3840 sc1
	v_mov_b64_e32 v[14:15], s[0:1]
	flat_load_dword v13, v[14:15] sc1
	v_mov_b64_e32 v[14:15], s[2:3]
	flat_load_dword v14, v[14:15] sc1
	v_mov_b64_e32 v[16:17], s[4:5]
	flat_load_dword v15, v[16:17] sc1
	v_mov_b64_e32 v[16:17], s[6:7]
	flat_load_dword v16, v[16:17] sc1
	v_readlane_b32 s16, v254, 12
	s_or_b64 s[14:15], s[14:15], exec
	s_or_b64 s[12:13], s[12:13], exec
	s_waitcnt vmcnt(0) lgkmcnt(0)
	v_add_u32_e32 v17, v0, v2
	v_add_u32_e32 v17, v17, v3
	v_add_u32_e32 v17, v17, v4
	v_add_u32_e32 v17, v17, v5
	v_add_u32_e32 v17, v17, v6
	v_add_u32_e32 v17, v17, v7
	v_add_u32_e32 v17, v17, v8
	v_add_u32_e32 v17, v17, v9
	v_add_u32_e32 v17, v17, v10
	v_add_u32_e32 v17, v17, v11
	v_add_u32_e32 v17, v17, v12
	v_add_u32_e32 v17, v17, v13
	v_add_u32_e32 v17, v17, v14
	v_add_u32_e32 v17, v17, v15
	v_add_u32_e32 v17, v17, v16
	v_cmp_ne_u32_e32 vcc, s16, v17
	s_and_saveexec_b64 s[16:17], vcc
	s_cbranch_execz .LBB0_1022
	s_and_b32 s20, s26, 0xff
	s_mov_b64 s[18:19], -1
	s_cmp_eq_u32 s20, 0
	s_mov_b64 s[22:23], -1
	s_mov_b64 s[20:21], -1
	s_cbranch_scc1 .LBB0_1026
	s_and_saveexec_b64 s[24:25], s[22:23]
	s_cbranch_execz .LBB0_1021
	s_branch .LBB0_1029

.LBB0_1037:
	s_and_b32 s14, s21, 0xff
	s_mov_b64 s[12:13], -1
	s_cmp_lg_u32 s14, 0
	s_mov_b64 s[14:15], -1
	s_cbranch_scc1 .LBB0_1041
	v_mov_b64_e32 v[4:5], s[34:35]
	flat_load_dword v0, v[4:5] offset:512 sc1
	s_mov_b64 s[14:15], 0
	s_mov_b64 s[16:17], -1
	s_waitcnt vmcnt(0) lgkmcnt(0)
	v_cmp_eq_u32_e32 vcc, 0, v0
	s_and_saveexec_b64 s[18:19], vcc
	s_cmp_lt_u32 s21, 0x40001
	s_cselect_b64 s[14:15], -1, 0
	s_xor_b64 s[16:17], exec, -1
	s_and_b64 s[14:15], s[14:15], exec
	s_or_b64 exec, exec, s[18:19]

.LBB0_1051:
	s_and_b32 s14, s21, 0xff
	s_mov_b64 s[12:13], -1
	s_cmp_lg_u32 s14, 0
	s_mov_b64 s[16:17], -1
	s_cbranch_scc0 .LBB0_1053
	s_and_saveexec_b64 s[18:19], s[16:17]
	s_cbranch_execz .LBB0_1050
	s_branch .LBB0_1056
